# ffn_in SwiGLU epilogue: packed v_pk_mul_f32 split into scalar multiplies, s_nops between dependent packed ops dropped
# speedup vs baseline: 1.0047x; 1.0005x over previous
.Lacq_done_f:
	v_readlane_b32 s0, v255, 40
	v_readlane_b32 s1, v255, 41
	v_readlane_b32 s2, v255, 42
	v_readlane_b32 s3, v255, 43
	v_readlane_b32 s4, v255, 44
	s_nop 3
	v_mul_f32_e32 v146, 0xbfb8aa3b, v126
	v_mul_f32_e32 v147, 0xbfb8aa3b, v127
	v_exp_f32_e32 v146, v146
	v_exp_f32_e32 v147, v147
	v_readlane_b32 s4, v254, 35
	v_lshl_add_u32 v143, s0, 8, v140
	v_add_f32_e32 v146, 1.0, v146
	v_add_f32_e32 v147, 1.0, v147
	v_rcp_f32_e32 v146, v146
	v_rcp_f32_e32 v147, v147
	s_lshl_b32 s0, s1, 7
	v_readlane_b32 s5, v254, 36
	s_ashr_i32 s1, s0, 31
	v_mul_f32_e32 v126, v126, v146
	v_mul_f32_e32 v127, v127, v147
	v_mov_b64_e32 v[138:139], s[4:5]
	v_mul_f32_e32 v122, v122, v126
	v_mul_f32_e32 v123, v123, v127
	v_mul_f32_e32 v126, 0xbfb8aa3b, v128
	v_mul_f32_e32 v127, 0xbfb8aa3b, v129
	v_exp_f32_e32 v126, v126
	v_exp_f32_e32 v127, v127
	s_movk_i32 s6, 0x1600
	v_mad_i64_i32 v[144:145], s[4:5], v143, s6, v[138:139]
	v_add_f32_e32 v126, 1.0, v126
	v_add_f32_e32 v127, 1.0, v127
	v_rcp_f32_e32 v126, v126
	v_rcp_f32_e32 v127, v127
	s_lshl_b64 s[0:1], s[0:1], 1
	v_readlane_b32 s8, v253, 49
	v_lshl_add_u64 v[144:145], v[144:145], 0, s[0:1]
	v_readlane_b32 s9, v253, 50
	v_mul_f32_e32 v126, v128, v126
	v_mul_f32_e32 v127, v129, v127
	v_cvt_pk_bf16_f32 v122, v122, v123
	v_lshl_add_u64 v[144:145], v[144:145], 0, s[8:9]
	v_mul_f32_e32 v124, v124, v126
	v_mul_f32_e32 v125, v125, v127
	v_lshl_add_u64 v[144:145], v[144:145], 0, v[0:1]
	v_cvt_pk_bf16_f32 v123, v124, v125
	global_store_dwordx2 v[144:145], v[122:123], off
	v_mul_f32_e32 v122, 0xbfb8aa3b, v118
	v_mul_f32_e32 v123, 0xbfb8aa3b, v119
	v_exp_f32_e32 v122, v122
	v_exp_f32_e32 v123, v123
	s_andn2_b64 vcc, exec, s[40:41]
	s_mov_b32 s39, 0xe7000
	v_add_f32_e32 v122, 1.0, v122
	v_add_f32_e32 v123, 1.0, v123
	v_rcp_f32_e32 v122, v122
	v_rcp_f32_e32 v123, v123
	s_mov_b64 s[48:49], 0xca00100
	v_mul_f32_e32 v118, v118, v122
	v_mul_f32_e32 v119, v119, v123
	v_mul_f32_e32 v114, v114, v118
	v_mul_f32_e32 v115, v115, v119
	v_mul_f32_e32 v118, 0xbfb8aa3b, v120
	v_mul_f32_e32 v119, 0xbfb8aa3b, v121
	v_exp_f32_e32 v118, v118
	v_exp_f32_e32 v119, v119
	v_cvt_pk_bf16_f32 v114, v114, v115
	v_add_f32_e32 v118, 1.0, v118
	v_add_f32_e32 v119, 1.0, v119
	v_rcp_f32_e32 v118, v118
	v_rcp_f32_e32 v119, v119
	s_nop 0
	v_mul_f32_e32 v118, v120, v118
	v_mul_f32_e32 v119, v121, v119
	v_mul_f32_e32 v116, v116, v118
	v_mul_f32_e32 v117, v117, v119
	v_cvt_pk_bf16_f32 v115, v116, v117
	v_mul_f32_e32 v116, 0xbfb8aa3b, v110
	v_mul_f32_e32 v117, 0xbfb8aa3b, v111
	v_exp_f32_e32 v116, v116
	v_exp_f32_e32 v117, v117
	global_store_dwordx2 v[144:145], v[114:115], off offset:32
	v_or_b32_e32 v114, 16, v143
	v_add_f32_e32 v116, 1.0, v116
	v_add_f32_e32 v117, 1.0, v117
	v_rcp_f32_e32 v116, v116
	v_rcp_f32_e32 v117, v117
	v_mad_i64_i32 v[114:115], s[4:5], v114, s6, v[138:139]
	v_lshl_add_u64 v[114:115], v[114:115], 0, s[0:1]
	v_mul_f32_e32 v110, v110, v116
	v_mul_f32_e32 v111, v111, v117
	v_lshl_add_u64 v[114:115], v[114:115], 0, s[8:9]
	v_mul_f32_e32 v106, v106, v110
	v_mul_f32_e32 v107, v107, v111
	v_mul_f32_e32 v110, 0xbfb8aa3b, v112
	v_mul_f32_e32 v111, 0xbfb8aa3b, v113
	v_exp_f32_e32 v110, v110
	v_exp_f32_e32 v111, v111
	v_lshl_add_u64 v[114:115], v[114:115], 0, v[0:1]
	v_cvt_pk_bf16_f32 v106, v106, v107
	v_add_f32_e32 v110, 1.0, v110
	v_add_f32_e32 v111, 1.0, v111
	v_rcp_f32_e32 v110, v110
	v_rcp_f32_e32 v111, v111
	s_nop 0
	v_mul_f32_e32 v110, v112, v110
	v_mul_f32_e32 v111, v113, v111
	v_mul_f32_e32 v108, v108, v110
	v_mul_f32_e32 v109, v109, v111
	v_cvt_pk_bf16_f32 v107, v108, v109
	global_store_dwordx2 v[114:115], v[106:107], off
	v_mul_f32_e32 v106, 0xbfb8aa3b, v102
	v_mul_f32_e32 v107, 0xbfb8aa3b, v103
	v_exp_f32_e32 v106, v106
	v_exp_f32_e32 v107, v107
	v_add_f32_e32 v106, 1.0, v106
	v_add_f32_e32 v107, 1.0, v107
	v_rcp_f32_e32 v106, v106
	v_rcp_f32_e32 v107, v107
	s_nop 0
	v_mul_f32_e32 v102, v102, v106
	v_mul_f32_e32 v103, v103, v107
	v_mul_f32_e32 v98, v98, v102
	v_mul_f32_e32 v99, v99, v103
	v_mul_f32_e32 v102, 0xbfb8aa3b, v104
	v_mul_f32_e32 v103, 0xbfb8aa3b, v105
	v_exp_f32_e32 v102, v102
	v_exp_f32_e32 v103, v103
	v_cvt_pk_bf16_f32 v98, v98, v99
	v_add_f32_e32 v102, 1.0, v102
	v_add_f32_e32 v103, 1.0, v103
	v_rcp_f32_e32 v102, v102
	v_rcp_f32_e32 v103, v103
	s_nop 0
	v_mul_f32_e32 v102, v104, v102
	v_mul_f32_e32 v103, v105, v103
	v_mul_f32_e32 v100, v100, v102
	v_mul_f32_e32 v101, v101, v103
	v_cvt_pk_bf16_f32 v99, v100, v101
	v_mul_f32_e32 v100, 0xbfb8aa3b, v94
	v_mul_f32_e32 v101, 0xbfb8aa3b, v95
	v_exp_f32_e32 v100, v100
	v_exp_f32_e32 v101, v101
	global_store_dwordx2 v[114:115], v[98:99], off offset:32
	v_or_b32_e32 v98, 32, v143
	v_add_f32_e32 v100, 1.0, v100
	v_add_f32_e32 v101, 1.0, v101
	v_rcp_f32_e32 v100, v100
	v_rcp_f32_e32 v101, v101
	v_mad_i64_i32 v[98:99], s[4:5], v98, s6, v[138:139]
	v_lshl_add_u64 v[98:99], v[98:99], 0, s[0:1]
	v_mul_f32_e32 v94, v94, v100
	v_mul_f32_e32 v95, v95, v101
	v_lshl_add_u64 v[98:99], v[98:99], 0, s[8:9]
	v_mul_f32_e32 v90, v90, v94
	v_mul_f32_e32 v91, v91, v95
	v_mul_f32_e32 v94, 0xbfb8aa3b, v96
	v_mul_f32_e32 v95, 0xbfb8aa3b, v97
	v_exp_f32_e32 v94, v94
	v_exp_f32_e32 v95, v95
	v_lshl_add_u64 v[98:99], v[98:99], 0, v[0:1]
	v_cvt_pk_bf16_f32 v90, v90, v91
	v_add_f32_e32 v94, 1.0, v94
	v_add_f32_e32 v95, 1.0, v95
	v_rcp_f32_e32 v94, v94
	v_rcp_f32_e32 v95, v95
	s_nop 0
	v_mul_f32_e32 v94, v96, v94
	v_mul_f32_e32 v95, v97, v95
	v_mul_f32_e32 v92, v92, v94
	v_mul_f32_e32 v93, v93, v95
	v_cvt_pk_bf16_f32 v91, v92, v93
	global_store_dwordx2 v[98:99], v[90:91], off
	v_mul_f32_e32 v90, 0xbfb8aa3b, v86
	v_mul_f32_e32 v91, 0xbfb8aa3b, v87
	v_exp_f32_e32 v90, v90
	v_exp_f32_e32 v91, v91
	v_add_f32_e32 v90, 1.0, v90
	v_add_f32_e32 v91, 1.0, v91
	v_rcp_f32_e32 v90, v90
	v_rcp_f32_e32 v91, v91
	s_nop 0
	v_mul_f32_e32 v86, v86, v90
	v_mul_f32_e32 v87, v87, v91
	v_mul_f32_e32 v82, v82, v86
	v_mul_f32_e32 v83, v83, v87
	v_mul_f32_e32 v86, 0xbfb8aa3b, v88
	v_mul_f32_e32 v87, 0xbfb8aa3b, v89
	v_exp_f32_e32 v86, v86
	v_exp_f32_e32 v87, v87
	v_cvt_pk_bf16_f32 v82, v82, v83
	v_add_f32_e32 v86, 1.0, v86
	v_add_f32_e32 v87, 1.0, v87
	v_rcp_f32_e32 v86, v86
	v_rcp_f32_e32 v87, v87
	s_nop 0
	v_mul_f32_e32 v86, v88, v86
	v_mul_f32_e32 v87, v89, v87
	v_mul_f32_e32 v84, v84, v86
	v_mul_f32_e32 v85, v85, v87
	v_cvt_pk_bf16_f32 v83, v84, v85
	v_mul_f32_e32 v84, 0xbfb8aa3b, v78
	v_mul_f32_e32 v85, 0xbfb8aa3b, v79
	v_exp_f32_e32 v84, v84
	v_exp_f32_e32 v85, v85
	global_store_dwordx2 v[98:99], v[82:83], off offset:32
	v_or_b32_e32 v82, 48, v143
	v_add_f32_e32 v84, 1.0, v84
	v_add_f32_e32 v85, 1.0, v85
	v_rcp_f32_e32 v84, v84
	v_rcp_f32_e32 v85, v85
	v_mad_i64_i32 v[82:83], s[4:5], v82, s6, v[138:139]
	v_lshl_add_u64 v[82:83], v[82:83], 0, s[0:1]
	v_mul_f32_e32 v78, v78, v84
	v_mul_f32_e32 v79, v79, v85
	v_lshl_add_u64 v[82:83], v[82:83], 0, s[8:9]
	v_mul_f32_e32 v74, v74, v78
	v_mul_f32_e32 v75, v75, v79
	v_mul_f32_e32 v78, 0xbfb8aa3b, v80
	v_mul_f32_e32 v79, 0xbfb8aa3b, v81
	v_exp_f32_e32 v78, v78
	v_exp_f32_e32 v79, v79
	v_lshl_add_u64 v[82:83], v[82:83], 0, v[0:1]
	v_cvt_pk_bf16_f32 v74, v74, v75
	v_add_f32_e32 v78, 1.0, v78
	v_add_f32_e32 v79, 1.0, v79
	v_rcp_f32_e32 v78, v78
	v_rcp_f32_e32 v79, v79
	s_nop 0
	v_mul_f32_e32 v78, v80, v78
	v_mul_f32_e32 v79, v81, v79
	v_mul_f32_e32 v76, v76, v78
	v_mul_f32_e32 v77, v77, v79
	v_cvt_pk_bf16_f32 v75, v76, v77
	global_store_dwordx2 v[82:83], v[74:75], off
	v_mul_f32_e32 v74, 0xbfb8aa3b, v70
	v_mul_f32_e32 v75, 0xbfb8aa3b, v71
	v_exp_f32_e32 v74, v74
	v_exp_f32_e32 v75, v75
	v_add_f32_e32 v74, 1.0, v74
	v_add_f32_e32 v75, 1.0, v75
	v_rcp_f32_e32 v74, v74
	v_rcp_f32_e32 v75, v75
	s_nop 0
	v_mul_f32_e32 v70, v70, v74
	v_mul_f32_e32 v71, v71, v75
	v_mul_f32_e32 v66, v66, v70
	v_mul_f32_e32 v67, v67, v71
	v_mul_f32_e32 v70, 0xbfb8aa3b, v72
	v_mul_f32_e32 v71, 0xbfb8aa3b, v73
	v_exp_f32_e32 v70, v70
	v_exp_f32_e32 v71, v71
	v_cvt_pk_bf16_f32 v66, v66, v67
	v_add_f32_e32 v70, 1.0, v70
	v_add_f32_e32 v71, 1.0, v71
	v_rcp_f32_e32 v70, v70
	v_rcp_f32_e32 v71, v71
	s_nop 0
	v_mul_f32_e32 v70, v72, v70
	v_mul_f32_e32 v71, v73, v71
	v_mul_f32_e32 v68, v68, v70
	v_mul_f32_e32 v69, v69, v71
	v_cvt_pk_bf16_f32 v67, v68, v69
	v_mul_f32_e32 v68, 0xbfb8aa3b, v62
	v_mul_f32_e32 v69, 0xbfb8aa3b, v63
	v_exp_f32_e32 v68, v68
	v_exp_f32_e32 v69, v69
	global_store_dwordx2 v[82:83], v[66:67], off offset:32
	v_add_u32_e32 v66, 0x80, v143
	v_add_f32_e32 v68, 1.0, v68
	v_add_f32_e32 v69, 1.0, v69
	v_rcp_f32_e32 v68, v68
	v_rcp_f32_e32 v69, v69
	v_mad_i64_i32 v[66:67], s[4:5], v66, s6, v[138:139]
	v_lshl_add_u64 v[66:67], v[66:67], 0, s[0:1]
	v_mul_f32_e32 v62, v62, v68
	v_mul_f32_e32 v63, v63, v69
	v_lshl_add_u64 v[66:67], v[66:67], 0, s[8:9]
	v_mul_f32_e32 v58, v58, v62
	v_mul_f32_e32 v59, v59, v63
	v_mul_f32_e32 v62, 0xbfb8aa3b, v64
	v_mul_f32_e32 v63, 0xbfb8aa3b, v65
	v_exp_f32_e32 v62, v62
	v_exp_f32_e32 v63, v63
	v_lshl_add_u64 v[66:67], v[66:67], 0, v[0:1]
	v_cvt_pk_bf16_f32 v58, v58, v59
	v_add_f32_e32 v62, 1.0, v62
	v_add_f32_e32 v63, 1.0, v63
	v_rcp_f32_e32 v62, v62
	v_rcp_f32_e32 v63, v63
	s_nop 0
	v_mul_f32_e32 v62, v64, v62
	v_mul_f32_e32 v63, v65, v63
	v_mul_f32_e32 v60, v60, v62
	v_mul_f32_e32 v61, v61, v63
	v_cvt_pk_bf16_f32 v59, v60, v61
	global_store_dwordx2 v[66:67], v[58:59], off
	v_mul_f32_e32 v58, 0xbfb8aa3b, v54
	v_mul_f32_e32 v59, 0xbfb8aa3b, v55
	v_exp_f32_e32 v58, v58
	v_exp_f32_e32 v59, v59
	v_add_f32_e32 v58, 1.0, v58
	v_add_f32_e32 v59, 1.0, v59
	v_rcp_f32_e32 v58, v58
	v_rcp_f32_e32 v59, v59
	s_nop 0
	v_mul_f32_e32 v54, v54, v58
	v_mul_f32_e32 v55, v55, v59
	v_mul_f32_e32 v50, v50, v54
	v_mul_f32_e32 v51, v51, v55
	v_mul_f32_e32 v54, 0xbfb8aa3b, v56
	v_mul_f32_e32 v55, 0xbfb8aa3b, v57
	v_exp_f32_e32 v54, v54
	v_exp_f32_e32 v55, v55
	v_cvt_pk_bf16_f32 v50, v50, v51
	v_add_f32_e32 v54, 1.0, v54
	v_add_f32_e32 v55, 1.0, v55
	v_rcp_f32_e32 v54, v54
	v_rcp_f32_e32 v55, v55
	s_nop 0
	v_mul_f32_e32 v54, v56, v54
	v_mul_f32_e32 v55, v57, v55
	v_mul_f32_e32 v52, v52, v54
	v_mul_f32_e32 v53, v53, v55
	v_cvt_pk_bf16_f32 v51, v52, v53
	v_mul_f32_e32 v52, 0xbfb8aa3b, v46
	v_mul_f32_e32 v53, 0xbfb8aa3b, v47
	v_exp_f32_e32 v52, v52
	v_exp_f32_e32 v53, v53
	global_store_dwordx2 v[66:67], v[50:51], off offset:32
	v_add_u32_e32 v50, 0x90, v143
	v_add_f32_e32 v52, 1.0, v52
	v_add_f32_e32 v53, 1.0, v53
	v_rcp_f32_e32 v52, v52
	v_rcp_f32_e32 v53, v53
	v_mad_i64_i32 v[50:51], s[4:5], v50, s6, v[138:139]
	v_lshl_add_u64 v[50:51], v[50:51], 0, s[0:1]
	v_mul_f32_e32 v46, v46, v52
	v_mul_f32_e32 v47, v47, v53
	v_lshl_add_u64 v[50:51], v[50:51], 0, s[8:9]
	v_mul_f32_e32 v42, v42, v46
	v_mul_f32_e32 v43, v43, v47
	v_mul_f32_e32 v46, 0xbfb8aa3b, v48
	v_mul_f32_e32 v47, 0xbfb8aa3b, v49
	v_exp_f32_e32 v46, v46
	v_exp_f32_e32 v47, v47
	v_lshl_add_u64 v[50:51], v[50:51], 0, v[0:1]
	v_cvt_pk_bf16_f32 v42, v42, v43
	v_add_f32_e32 v46, 1.0, v46
	v_add_f32_e32 v47, 1.0, v47
	v_rcp_f32_e32 v46, v46
	v_rcp_f32_e32 v47, v47
	s_nop 0
	v_mul_f32_e32 v46, v48, v46
	v_mul_f32_e32 v47, v49, v47
	v_mul_f32_e32 v44, v44, v46
	v_mul_f32_e32 v45, v45, v47
	v_cvt_pk_bf16_f32 v43, v44, v45
	global_store_dwordx2 v[50:51], v[42:43], off
	v_mul_f32_e32 v42, 0xbfb8aa3b, v38
	v_mul_f32_e32 v43, 0xbfb8aa3b, v39
	v_exp_f32_e32 v42, v42
	v_exp_f32_e32 v43, v43
	v_add_f32_e32 v42, 1.0, v42
	v_add_f32_e32 v43, 1.0, v43
	v_rcp_f32_e32 v42, v42
	v_rcp_f32_e32 v43, v43
	s_nop 0
	v_mul_f32_e32 v38, v38, v42
	v_mul_f32_e32 v39, v39, v43
	v_mul_f32_e32 v34, v34, v38
	v_mul_f32_e32 v35, v35, v39
	v_mul_f32_e32 v38, 0xbfb8aa3b, v40
	v_mul_f32_e32 v39, 0xbfb8aa3b, v41
	v_exp_f32_e32 v38, v38
	v_exp_f32_e32 v39, v39
	v_cvt_pk_bf16_f32 v34, v34, v35
	v_add_f32_e32 v38, 1.0, v38
	v_add_f32_e32 v39, 1.0, v39
	v_rcp_f32_e32 v38, v38
	v_rcp_f32_e32 v39, v39
	s_nop 0
	v_mul_f32_e32 v38, v40, v38
	v_mul_f32_e32 v39, v41, v39
	v_mul_f32_e32 v36, v36, v38
	v_mul_f32_e32 v37, v37, v39
	v_cvt_pk_bf16_f32 v35, v36, v37
	v_mul_f32_e32 v36, 0xbfb8aa3b, v30
	v_mul_f32_e32 v37, 0xbfb8aa3b, v31
	v_exp_f32_e32 v36, v36
	v_exp_f32_e32 v37, v37
	global_store_dwordx2 v[50:51], v[34:35], off offset:32
	v_add_u32_e32 v34, 0xa0, v143
	v_add_f32_e32 v36, 1.0, v36
	v_add_f32_e32 v37, 1.0, v37
	v_rcp_f32_e32 v36, v36
	v_rcp_f32_e32 v37, v37
	v_mad_i64_i32 v[34:35], s[4:5], v34, s6, v[138:139]
	v_lshl_add_u64 v[34:35], v[34:35], 0, s[0:1]
	v_mul_f32_e32 v30, v30, v36
	v_mul_f32_e32 v31, v31, v37
	v_lshl_add_u64 v[34:35], v[34:35], 0, s[8:9]
	v_mul_f32_e32 v26, v26, v30
	v_mul_f32_e32 v27, v27, v31
	v_mul_f32_e32 v30, 0xbfb8aa3b, v32
	v_mul_f32_e32 v31, 0xbfb8aa3b, v33
	v_exp_f32_e32 v30, v30
	v_exp_f32_e32 v31, v31
	v_lshl_add_u64 v[34:35], v[34:35], 0, v[0:1]
	v_cvt_pk_bf16_f32 v26, v26, v27
	v_add_f32_e32 v30, 1.0, v30
	v_add_f32_e32 v31, 1.0, v31
	v_rcp_f32_e32 v30, v30
	v_rcp_f32_e32 v31, v31
	s_nop 0
	v_mul_f32_e32 v30, v32, v30
	v_mul_f32_e32 v31, v33, v31
	v_mul_f32_e32 v28, v28, v30
	v_mul_f32_e32 v29, v29, v31
	v_cvt_pk_bf16_f32 v27, v28, v29
	global_store_dwordx2 v[34:35], v[26:27], off
	v_mul_f32_e32 v26, 0xbfb8aa3b, v22
	v_mul_f32_e32 v27, 0xbfb8aa3b, v23
	v_exp_f32_e32 v26, v26
	v_exp_f32_e32 v27, v27
	v_add_f32_e32 v26, 1.0, v26
	v_add_f32_e32 v27, 1.0, v27
	v_rcp_f32_e32 v26, v26
	v_rcp_f32_e32 v27, v27
	s_nop 0
	v_mul_f32_e32 v22, v22, v26
	v_mul_f32_e32 v23, v23, v27
	v_mul_f32_e32 v18, v18, v22
	v_mul_f32_e32 v19, v19, v23
	v_mul_f32_e32 v22, 0xbfb8aa3b, v24
	v_mul_f32_e32 v23, 0xbfb8aa3b, v25
	v_exp_f32_e32 v22, v22
	v_exp_f32_e32 v23, v23
	v_cvt_pk_bf16_f32 v18, v18, v19
	v_add_f32_e32 v22, 1.0, v22
	v_add_f32_e32 v23, 1.0, v23
	v_rcp_f32_e32 v22, v22
	v_rcp_f32_e32 v23, v23
	s_nop 0
	v_mul_f32_e32 v22, v24, v22
	v_mul_f32_e32 v23, v25, v23
	v_mul_f32_e32 v20, v20, v22
	v_mul_f32_e32 v21, v21, v23
	v_cvt_pk_bf16_f32 v19, v20, v21
	v_mul_f32_e32 v20, 0xbfb8aa3b, v14
	v_mul_f32_e32 v21, 0xbfb8aa3b, v15
	v_exp_f32_e32 v20, v20
	v_exp_f32_e32 v21, v21
	global_store_dwordx2 v[34:35], v[18:19], off offset:32
	v_add_u32_e32 v18, 0xb0, v143
	v_add_f32_e32 v20, 1.0, v20
	v_add_f32_e32 v21, 1.0, v21
	v_rcp_f32_e32 v20, v20
	v_rcp_f32_e32 v21, v21
	v_mad_i64_i32 v[18:19], s[4:5], v18, s6, v[138:139]
	v_lshl_add_u64 v[18:19], v[18:19], 0, s[0:1]
	v_mul_f32_e32 v14, v14, v20
	v_mul_f32_e32 v15, v15, v21
	v_lshl_add_u64 v[18:19], v[18:19], 0, s[8:9]
	v_mul_f32_e32 v10, v10, v14
	v_mul_f32_e32 v11, v11, v15
	v_mul_f32_e32 v14, 0xbfb8aa3b, v16
	v_mul_f32_e32 v15, 0xbfb8aa3b, v17
	v_exp_f32_e32 v14, v14
	v_exp_f32_e32 v15, v15
	v_lshl_add_u64 v[18:19], v[18:19], 0, v[0:1]
	v_cvt_pk_bf16_f32 v10, v10, v11
	v_add_f32_e32 v14, 1.0, v14
	v_add_f32_e32 v15, 1.0, v15
	v_rcp_f32_e32 v14, v14
	v_rcp_f32_e32 v15, v15
	s_mov_b64 s[0:1], -1
	v_mul_f32_e32 v14, v16, v14
	v_mul_f32_e32 v15, v17, v15
	v_mul_f32_e32 v12, v12, v14
	v_mul_f32_e32 v13, v13, v15
	v_cvt_pk_bf16_f32 v11, v12, v13
	global_store_dwordx2 v[18:19], v[10:11], off
	v_mul_f32_e32 v10, 0xbfb8aa3b, v6
	v_mul_f32_e32 v11, 0xbfb8aa3b, v7
	v_exp_f32_e32 v10, v10
	v_exp_f32_e32 v11, v11
	v_add_f32_e32 v10, 1.0, v10
	v_add_f32_e32 v11, 1.0, v11
	v_rcp_f32_e32 v10, v10
	v_rcp_f32_e32 v11, v11
	s_nop 0
	v_mul_f32_e32 v6, v6, v10
	v_mul_f32_e32 v7, v7, v11
	v_mul_f32_e32 v2, v2, v6
	v_mul_f32_e32 v3, v3, v7
	v_mul_f32_e32 v6, 0xbfb8aa3b, v8
	v_mul_f32_e32 v7, 0xbfb8aa3b, v9
	v_exp_f32_e32 v6, v6
	v_exp_f32_e32 v7, v7
	v_cvt_pk_bf16_f32 v2, v2, v3
	v_add_f32_e32 v6, 1.0, v6
	v_add_f32_e32 v7, 1.0, v7
	v_rcp_f32_e32 v6, v6
	v_rcp_f32_e32 v7, v7
	s_nop 0
	v_mul_f32_e32 v6, v8, v6
	v_mul_f32_e32 v7, v9, v7
	v_mul_f32_e32 v4, v4, v6
	v_mul_f32_e32 v5, v5, v7
	v_cvt_pk_bf16_f32 v3, v4, v5
	global_store_dwordx2 v[18:19], v[2:3], off offset:32
	s_cbranch_vccnz .LBB0_912
	s_andn2_b64 vcc, exec, s[36:37]
	s_cbranch_vccnz .LBB0_911
	s_barrier
	s_branch .LBB0_911
